# S2 gelu epilogue row groups 2-16 hand-written (7 VALU/output, interleaved, folded constants)
# speedup vs baseline: 1.0003x; 1.0003x over previous
; __device__ __forceinline__ unsigned cvt_pk_bf16(float lo, float hi) { unsigned r; asm volatile("v_cvt_pk_bf16_f32 %0, %1, %2" : "=v"(r) : "v"(lo), "v"(hi)); return r; }
; __device__ __forceinline__ float sigmoid_f(float x) { return __builtin_amdgcn_rcpf(1.0f + __builtin_amdgcn_exp2f(-1.4426950408889634f * x)); }
;     __device__ __forceinline__ void operator()(const f32x4 (&acc)[2][2][4][2], const pg8::Unit& u, int wr, int wc, int fr, int fq, LAS unsigned char* lds, int wid, int lane, const pg8::Unit& nxt, bool has_next, int ui) const {
;     ...
;                 const int tok0 = (rl0 + ai * 128 + m * 16) * TC;
; #pragma unroll
;                 for (int bj = 0; bj < 2; ++bj) {
;                     const int t = 16 * pnl + 8 * bj + 2 * wc + (fq >> 1), h0 = 8 * (fq & 1);
;                     float o[8];
; #pragma unroll
;                     for (int e = 0; e < 8; ++e) { const float y = acc[ai][bj][m][e >> 2][e & 3]; o[e] = y * sigmoid_f(1.5957691216f * y * (1.0f + 0.044715f * y * y)); }
;                     v4u w; w.x = cvt_pk_bf16(o[0], o[1]); w.y = cvt_pk_bf16(o[2], o[3]); w.z = cvt_pk_bf16(o[4], o[5]); w.w = cvt_pk_bf16(o[6], o[7]);
;                     *(v4u*)(Z + ((size_t)(tok0 + t) * SW + gg * 16 + h0)) = w;
;                 }
.LBB0_259:
	v_mul_f32_e32 v149, 0x3d372713, v127
	v_mul_f32_e32 v148, 0x3fcc422a, v127
	v_fma_f32 v149, v127, v149, 1.0
	v_mul_f32_e32 v150, 0x3d372713, v128
	v_mul_f32_e32 v145, 0x3d372713, v126
	v_mul_f32_e32 v148, v148, v149
	v_mul_f32_e32 v149, 0x3fcc422a, v128
	v_fma_f32 v150, v128, v150, 1.0
	v_mul_f32_e32 v144, 0x3fcc422a, v126
	v_fma_f32 v145, v126, v145, 1.0
	v_mul_f32_e32 v149, v149, v150
	v_mul_f32_e32 v144, v144, v145
	v_mul_f32_e32 v149, 0xbfb8aa3b, v149
	v_mul_f32_e32 v144, 0xbfb8aa3b, v144
	v_mul_f32_e32 v148, 0xbfb8aa3b, v148
	v_exp_f32_e32 v149, v149
	v_exp_f32_e32 v145, v144
	v_exp_f32_e32 v148, v148
	v_mul_f32_e32 v151, 0x3d372713, v129
	v_mul_f32_e32 v150, 0x3fcc422a, v129
	v_fma_f32 v151, v129, v151, 1.0
	v_add_f32_e32 v149, 1.0, v149
	v_mul_f32_e32 v150, v150, v151
	v_add_f32_e32 v145, 1.0, v145
	v_add_f32_e32 v148, 1.0, v148
	v_rcp_f32_e32 v149, v149
	v_mul_f32_e32 v150, 0xbfb8aa3b, v150
	v_rcp_f32_e32 v145, v145
	v_rcp_f32_e32 v148, v148
	v_exp_f32_e32 v150, v150
	v_mul_f32_e32 v128, v128, v149
	v_mul_f32_e32 v149, 0x3d372713, v122
	v_mul_f32_e32 v126, v126, v145
	v_mul_f32_e32 v127, v127, v148
	v_add_f32_e32 v145, 1.0, v150
	v_mul_f32_e32 v148, 0x3fcc422a, v122
	v_fma_f32 v149, v122, v149, 1.0
	v_mul_f32_e32 v150, 0x3d372713, v123
	v_mul_f32_e32 v148, v148, v149
	v_mul_f32_e32 v149, 0x3fcc422a, v123
	v_fma_f32 v150, v123, v150, 1.0
	v_mul_f32_e32 v149, v149, v150
	v_mul_f32_e32 v148, 0xbfb8aa3b, v148
	v_mul_f32_e32 v149, 0xbfb8aa3b, v149
	v_rcp_f32_e32 v145, v145
	v_exp_f32_e32 v148, v148
	v_exp_f32_e32 v149, v149
	v_mul_f32_e32 v150, 0x3d372713, v124
	v_mul_f32_e32 v129, v129, v145
	v_add_f32_e32 v145, 1.0, v148
	v_add_f32_e32 v148, 1.0, v149
	v_mul_f32_e32 v149, 0x3fcc422a, v124
	v_fma_f32 v150, v124, v150, 1.0
	v_mul_f32_e32 v149, v149, v150
	v_mul_f32_e32 v151, 0x3d372713, v125
	v_mul_f32_e32 v149, 0xbfb8aa3b, v149
	v_mul_f32_e32 v150, 0x3fcc422a, v125
	v_fma_f32 v151, v125, v151, 1.0
	v_exp_f32_e32 v149, v149
	v_mul_f32_e32 v150, v150, v151
	v_mul_f32_e32 v150, 0xbfb8aa3b, v150
	v_rcp_f32_e32 v145, v145
	v_exp_f32_e32 v150, v150
	v_add_f32_e32 v149, 1.0, v149
	v_rcp_f32_e32 v148, v148
	v_rcp_f32_e32 v149, v149
	v_add_f32_e32 v150, 1.0, v150
	v_mul_f32_e32 v145, v122, v145
	v_cvt_pk_bf16_f32 v122, v126, v127
	v_mul_f32_e32 v127, 0x3d372713, v118
	v_rcp_f32_e32 v150, v150
	v_mul_f32_e32 v126, 0x3fcc422a, v118
	v_fma_f32 v127, v118, v127, 1.0
	v_or_b32_e32 v144, s33, v146
	v_mul_f32_e32 v126, v126, v127
	v_mul_f32_e32 v148, v123, v148
	v_mul_f32_e32 v149, v124, v149
	v_cvt_pk_bf16_f32 v123, v128, v129
	v_cvt_pk_bf16_f32 v124, v145, v148
	v_ashrrev_i32_e32 v145, 31, v144
	v_mul_f32_e32 v126, 0xbfb8aa3b, v126
	v_exp_f32_e32 v128, v126
	v_lshlrev_b64 v[126:127], 10, v[144:145]
	v_mul_f32_e32 v125, v125, v150
	v_lshl_add_u64 v[126:127], v[138:139], 0, v[126:127]
	v_cvt_pk_bf16_f32 v125, v149, v125
	global_store_dwordx4 v[126:127], v[122:125], off
	v_mov_b32_e32 v232, 0xbdd2d3e8
	v_mov_b32_e32 v235, 0
	v_mul_f32_e32 v224, v118, v118
	v_mul_f32_e32 v225, v119, v119
	v_mul_f32_e32 v226, v120, v120
	v_mul_f32_e32 v227, v121, v121
	v_mul_f32_e32 v228, v114, v114
	v_mul_f32_e32 v229, v115, v115
	v_mul_f32_e32 v230, v116, v116
	v_mul_f32_e32 v231, v117, v117
	v_fmaak_f32 v224, v232, v224, 0xc0135761
	v_fmaak_f32 v225, v232, v225, 0xc0135761
	v_fmaak_f32 v226, v232, v226, 0xc0135761
	v_fmaak_f32 v227, v232, v227, 0xc0135761
	v_fmaak_f32 v228, v232, v228, 0xc0135761
	v_fmaak_f32 v229, v232, v229, 0xc0135761
	v_fmaak_f32 v230, v232, v230, 0xc0135761
	v_fmaak_f32 v231, v232, v231, 0xc0135761
	v_mul_f32_e32 v224, v224, v118
	v_mul_f32_e32 v225, v225, v119
	v_mul_f32_e32 v226, v226, v120
	v_mul_f32_e32 v227, v227, v121
	v_mul_f32_e32 v228, v228, v114
	v_mul_f32_e32 v229, v229, v115
	v_mul_f32_e32 v230, v230, v116
	v_mul_f32_e32 v231, v231, v117
	v_exp_f32_e32 v224, v224
	v_exp_f32_e32 v225, v225
	v_exp_f32_e32 v226, v226
	v_exp_f32_e32 v227, v227
	v_exp_f32_e32 v228, v228
	v_exp_f32_e32 v229, v229
	v_exp_f32_e32 v230, v230
	v_exp_f32_e32 v231, v231
	v_add_f32_e32 v224, 1.0, v224
	v_add_f32_e32 v225, 1.0, v225
	v_add_f32_e32 v226, 1.0, v226
	v_add_f32_e32 v227, 1.0, v227
	v_add_f32_e32 v228, 1.0, v228
	v_add_f32_e32 v229, 1.0, v229
	v_add_f32_e32 v230, 1.0, v230
	v_add_f32_e32 v231, 1.0, v231
	v_rcp_f32_e32 v224, v224
	v_rcp_f32_e32 v225, v225
	v_rcp_f32_e32 v226, v226
	v_rcp_f32_e32 v227, v227
	v_rcp_f32_e32 v228, v228
	v_rcp_f32_e32 v229, v229
	v_rcp_f32_e32 v230, v230
	v_rcp_f32_e32 v231, v231
	v_mul_f32_e32 v118, v118, v224
	v_mul_f32_e32 v119, v119, v225
	v_mul_f32_e32 v120, v120, v226
	v_mul_f32_e32 v121, v121, v227
	v_mul_f32_e32 v114, v114, v228
	v_mul_f32_e32 v115, v115, v229
	v_mul_f32_e32 v116, v116, v230
	v_mul_f32_e32 v117, v117, v231
	v_cvt_pk_bf16_f32 v118, v118, v119
	v_cvt_pk_bf16_f32 v119, v120, v121
	v_cvt_pk_bf16_f32 v120, v114, v115
	v_cvt_pk_bf16_f32 v121, v116, v117
	v_add_u32_e32 v233, 8, v144
	v_lshlrev_b32_e32 v234, 10, v233
	v_lshl_add_u64 v[236:237], v[138:139], 0, v[234:235]
	global_store_dwordx4 v[236:237], v[118:121], off
	v_mul_f32_e32 v224, v110, v110
	v_mul_f32_e32 v225, v111, v111
	v_mul_f32_e32 v226, v112, v112
	v_mul_f32_e32 v227, v113, v113
	v_mul_f32_e32 v228, v106, v106
	v_mul_f32_e32 v229, v107, v107
	v_mul_f32_e32 v230, v108, v108
	v_mul_f32_e32 v231, v109, v109
	v_fmaak_f32 v224, v232, v224, 0xc0135761
	v_fmaak_f32 v225, v232, v225, 0xc0135761
	v_fmaak_f32 v226, v232, v226, 0xc0135761
	v_fmaak_f32 v227, v232, v227, 0xc0135761
	v_fmaak_f32 v228, v232, v228, 0xc0135761
	v_fmaak_f32 v229, v232, v229, 0xc0135761
	v_fmaak_f32 v230, v232, v230, 0xc0135761
	v_fmaak_f32 v231, v232, v231, 0xc0135761
; __device__ __forceinline__ unsigned cvt_pk_bf16(float lo, float hi) { unsigned r; asm volatile("v_cvt_pk_bf16_f32 %0, %1, %2" : "=v"(r) : "v"(lo), "v"(hi)); return r; }
; __device__ __forceinline__ float sigmoid_f(float x) { return __builtin_amdgcn_rcpf(1.0f + __builtin_amdgcn_exp2f(-1.4426950408889634f * x)); }
;     __device__ __forceinline__ void operator()(const f32x4 (&acc)[2][2][4][2], const pg8::Unit& u, int wr, int wc, int fr, int fq, LAS unsigned char* lds, int wid, int lane, const pg8::Unit& nxt, bool has_next, int ui) const {
;     ...
;                 const int tok0 = (rl0 + ai * 128 + m * 16) * TC;
; #pragma unroll
;                 for (int bj = 0; bj < 2; ++bj) {
;                     const int t = 16 * pnl + 8 * bj + 2 * wc + (fq >> 1), h0 = 8 * (fq & 1);
;                     float o[8];
; #pragma unroll
;                     for (int e = 0; e < 8; ++e) { const float y = acc[ai][bj][m][e >> 2][e & 3]; o[e] = y * sigmoid_f(1.5957691216f * y * (1.0f + 0.044715f * y * y)); }
;                     v4u w; w.x = cvt_pk_bf16(o[0], o[1]); w.y = cvt_pk_bf16(o[2], o[3]); w.z = cvt_pk_bf16(o[4], o[5]); w.w = cvt_pk_bf16(o[6], o[7]);
;                     *(v4u*)(Z + ((size_t)(tok0 + t) * SW + gg * 16 + h0)) = w;
;                 }
	v_mul_f32_e32 v224, v224, v110
	v_mul_f32_e32 v225, v225, v111
	v_mul_f32_e32 v226, v226, v112
	v_mul_f32_e32 v227, v227, v113
	v_mul_f32_e32 v228, v228, v106
	v_mul_f32_e32 v229, v229, v107
	v_mul_f32_e32 v230, v230, v108
	v_mul_f32_e32 v231, v231, v109
	v_exp_f32_e32 v224, v224
	v_exp_f32_e32 v225, v225
	v_exp_f32_e32 v226, v226
	v_exp_f32_e32 v227, v227
	v_exp_f32_e32 v228, v228
	v_exp_f32_e32 v229, v229
	v_exp_f32_e32 v230, v230
	v_exp_f32_e32 v231, v231
	v_add_f32_e32 v224, 1.0, v224
	v_add_f32_e32 v225, 1.0, v225
	v_add_f32_e32 v226, 1.0, v226
	v_add_f32_e32 v227, 1.0, v227
	v_add_f32_e32 v228, 1.0, v228
	v_add_f32_e32 v229, 1.0, v229
	v_add_f32_e32 v230, 1.0, v230
	v_add_f32_e32 v231, 1.0, v231
	v_rcp_f32_e32 v224, v224
	v_rcp_f32_e32 v225, v225
	v_rcp_f32_e32 v226, v226
	v_rcp_f32_e32 v227, v227
	v_rcp_f32_e32 v228, v228
	v_rcp_f32_e32 v229, v229
	v_rcp_f32_e32 v230, v230
	v_rcp_f32_e32 v231, v231
	v_mul_f32_e32 v110, v110, v224
	v_mul_f32_e32 v111, v111, v225
	v_mul_f32_e32 v112, v112, v226
	v_mul_f32_e32 v113, v113, v227
	v_mul_f32_e32 v106, v106, v228
	v_mul_f32_e32 v107, v107, v229
	v_mul_f32_e32 v108, v108, v230
	v_mul_f32_e32 v109, v109, v231
	v_cvt_pk_bf16_f32 v110, v110, v111
	v_cvt_pk_bf16_f32 v111, v112, v113
	v_cvt_pk_bf16_f32 v112, v106, v107
	v_cvt_pk_bf16_f32 v113, v108, v109
	v_add_u32_e32 v233, 0x200, v144
	v_lshlrev_b32_e32 v234, 10, v233
	v_lshl_add_u64 v[236:237], v[138:139], 0, v[234:235]
	global_store_dwordx4 v[236:237], v[110:113], off
	v_mul_f32_e32 v224, v102, v102
	v_mul_f32_e32 v225, v103, v103
	v_mul_f32_e32 v226, v104, v104
	v_mul_f32_e32 v227, v105, v105
	v_mul_f32_e32 v228, v98, v98
	v_mul_f32_e32 v229, v99, v99
	v_mul_f32_e32 v230, v100, v100
	v_mul_f32_e32 v231, v101, v101
	v_fmaak_f32 v224, v232, v224, 0xc0135761
	v_fmaak_f32 v225, v232, v225, 0xc0135761
	v_fmaak_f32 v226, v232, v226, 0xc0135761
	v_fmaak_f32 v227, v232, v227, 0xc0135761
	v_fmaak_f32 v228, v232, v228, 0xc0135761
	v_fmaak_f32 v229, v232, v229, 0xc0135761
	v_fmaak_f32 v230, v232, v230, 0xc0135761
	v_fmaak_f32 v231, v232, v231, 0xc0135761
	v_mul_f32_e32 v224, v224, v102
	v_mul_f32_e32 v225, v225, v103
	v_mul_f32_e32 v226, v226, v104
	v_mul_f32_e32 v227, v227, v105
	v_mul_f32_e32 v228, v228, v98
	v_mul_f32_e32 v229, v229, v99
	v_mul_f32_e32 v230, v230, v100
	v_mul_f32_e32 v231, v231, v101
	v_exp_f32_e32 v224, v224
	v_exp_f32_e32 v225, v225
	v_exp_f32_e32 v226, v226
	v_exp_f32_e32 v227, v227
	v_exp_f32_e32 v228, v228
	v_exp_f32_e32 v229, v229
	v_exp_f32_e32 v230, v230
	v_exp_f32_e32 v231, v231
	v_add_f32_e32 v224, 1.0, v224
	v_add_f32_e32 v225, 1.0, v225
	v_add_f32_e32 v226, 1.0, v226
	v_add_f32_e32 v227, 1.0, v227
	v_add_f32_e32 v228, 1.0, v228
	v_add_f32_e32 v229, 1.0, v229
	v_add_f32_e32 v230, 1.0, v230
	v_add_f32_e32 v231, 1.0, v231
	v_rcp_f32_e32 v224, v224
	v_rcp_f32_e32 v225, v225
	v_rcp_f32_e32 v226, v226
	v_rcp_f32_e32 v227, v227
	v_rcp_f32_e32 v228, v228
	v_rcp_f32_e32 v229, v229
	v_rcp_f32_e32 v230, v230
	v_rcp_f32_e32 v231, v231
	v_mul_f32_e32 v102, v102, v224
	v_mul_f32_e32 v103, v103, v225
	v_mul_f32_e32 v104, v104, v226
	v_mul_f32_e32 v105, v105, v227
	v_mul_f32_e32 v98, v98, v228
	v_mul_f32_e32 v99, v99, v229
	v_mul_f32_e32 v100, v100, v230
	v_mul_f32_e32 v101, v101, v231
	v_cvt_pk_bf16_f32 v102, v102, v103
	v_cvt_pk_bf16_f32 v103, v104, v105
	v_cvt_pk_bf16_f32 v104, v98, v99
	v_cvt_pk_bf16_f32 v105, v100, v101
	v_add_u32_e32 v233, 0x208, v144
	v_lshlrev_b32_e32 v234, 10, v233
	v_lshl_add_u64 v[236:237], v[138:139], 0, v[234:235]
	global_store_dwordx4 v[236:237], v[102:105], off
	v_mul_f32_e32 v224, v94, v94
	v_mul_f32_e32 v225, v95, v95
	v_mul_f32_e32 v226, v96, v96
	v_mul_f32_e32 v227, v97, v97
	v_mul_f32_e32 v228, v90, v90
	v_mul_f32_e32 v229, v91, v91
	v_mul_f32_e32 v230, v92, v92
	v_mul_f32_e32 v231, v93, v93
	v_fmaak_f32 v224, v232, v224, 0xc0135761
	v_fmaak_f32 v225, v232, v225, 0xc0135761
	v_fmaak_f32 v226, v232, v226, 0xc0135761
	v_fmaak_f32 v227, v232, v227, 0xc0135761
	v_fmaak_f32 v228, v232, v228, 0xc0135761
	v_fmaak_f32 v229, v232, v229, 0xc0135761
	v_fmaak_f32 v230, v232, v230, 0xc0135761
	v_fmaak_f32 v231, v232, v231, 0xc0135761
	v_mul_f32_e32 v224, v224, v94
	v_mul_f32_e32 v225, v225, v95
	v_mul_f32_e32 v226, v226, v96
	v_mul_f32_e32 v227, v227, v97
	v_mul_f32_e32 v228, v228, v90
	v_mul_f32_e32 v229, v229, v91
	v_mul_f32_e32 v230, v230, v92
	v_mul_f32_e32 v231, v231, v93
	v_exp_f32_e32 v224, v224
	v_exp_f32_e32 v225, v225
	v_exp_f32_e32 v226, v226
	v_exp_f32_e32 v227, v227
	v_exp_f32_e32 v228, v228
	v_exp_f32_e32 v229, v229
	v_exp_f32_e32 v230, v230
	v_exp_f32_e32 v231, v231
	v_add_f32_e32 v224, 1.0, v224
	v_add_f32_e32 v225, 1.0, v225
	v_add_f32_e32 v226, 1.0, v226
	v_add_f32_e32 v227, 1.0, v227
	v_add_f32_e32 v228, 1.0, v228
	v_add_f32_e32 v229, 1.0, v229
	v_add_f32_e32 v230, 1.0, v230
	v_add_f32_e32 v231, 1.0, v231
	v_rcp_f32_e32 v224, v224
	v_rcp_f32_e32 v225, v225
	v_rcp_f32_e32 v226, v226
	v_rcp_f32_e32 v227, v227
	v_rcp_f32_e32 v228, v228
	v_rcp_f32_e32 v229, v229
	v_rcp_f32_e32 v230, v230
	v_rcp_f32_e32 v231, v231
	v_mul_f32_e32 v94, v94, v224
	v_mul_f32_e32 v95, v95, v225
	v_mul_f32_e32 v96, v96, v226
	v_mul_f32_e32 v97, v97, v227
	v_mul_f32_e32 v90, v90, v228
	v_mul_f32_e32 v91, v91, v229
	v_mul_f32_e32 v92, v92, v230
	v_mul_f32_e32 v93, v93, v231
	v_cvt_pk_bf16_f32 v94, v94, v95
	v_cvt_pk_bf16_f32 v95, v96, v97
	v_cvt_pk_bf16_f32 v96, v90, v91
	v_cvt_pk_bf16_f32 v97, v92, v93
	v_add_u32_e32 v233, 0x400, v144
	v_lshlrev_b32_e32 v234, 10, v233
	v_lshl_add_u64 v[236:237], v[138:139], 0, v[234:235]
	global_store_dwordx4 v[236:237], v[94:97], off
	v_mul_f32_e32 v224, v86, v86
	v_mul_f32_e32 v225, v87, v87
; __device__ __forceinline__ unsigned cvt_pk_bf16(float lo, float hi) { unsigned r; asm volatile("v_cvt_pk_bf16_f32 %0, %1, %2" : "=v"(r) : "v"(lo), "v"(hi)); return r; }
; __device__ __forceinline__ float sigmoid_f(float x) { return __builtin_amdgcn_rcpf(1.0f + __builtin_amdgcn_exp2f(-1.4426950408889634f * x)); }
;     __device__ __forceinline__ void operator()(const f32x4 (&acc)[2][2][4][2], const pg8::Unit& u, int wr, int wc, int fr, int fq, LAS unsigned char* lds, int wid, int lane, const pg8::Unit& nxt, bool has_next, int ui) const {
;     ...
;                 const int tok0 = (rl0 + ai * 128 + m * 16) * TC;
; #pragma unroll
;                 for (int bj = 0; bj < 2; ++bj) {
;                     const int t = 16 * pnl + 8 * bj + 2 * wc + (fq >> 1), h0 = 8 * (fq & 1);
;                     float o[8];
; #pragma unroll
;                     for (int e = 0; e < 8; ++e) { const float y = acc[ai][bj][m][e >> 2][e & 3]; o[e] = y * sigmoid_f(1.5957691216f * y * (1.0f + 0.044715f * y * y)); }
;                     v4u w; w.x = cvt_pk_bf16(o[0], o[1]); w.y = cvt_pk_bf16(o[2], o[3]); w.z = cvt_pk_bf16(o[4], o[5]); w.w = cvt_pk_bf16(o[6], o[7]);
;                     *(v4u*)(Z + ((size_t)(tok0 + t) * SW + gg * 16 + h0)) = w;
;                 }
	v_mul_f32_e32 v226, v88, v88
	v_mul_f32_e32 v227, v89, v89
	v_mul_f32_e32 v228, v82, v82
	v_mul_f32_e32 v229, v83, v83
	v_mul_f32_e32 v230, v84, v84
	v_mul_f32_e32 v231, v85, v85
	v_fmaak_f32 v224, v232, v224, 0xc0135761
	v_fmaak_f32 v225, v232, v225, 0xc0135761
	v_fmaak_f32 v226, v232, v226, 0xc0135761
	v_fmaak_f32 v227, v232, v227, 0xc0135761
	v_fmaak_f32 v228, v232, v228, 0xc0135761
	v_fmaak_f32 v229, v232, v229, 0xc0135761
	v_fmaak_f32 v230, v232, v230, 0xc0135761
	v_fmaak_f32 v231, v232, v231, 0xc0135761
	v_mul_f32_e32 v224, v224, v86
	v_mul_f32_e32 v225, v225, v87
	v_mul_f32_e32 v226, v226, v88
	v_mul_f32_e32 v227, v227, v89
	v_mul_f32_e32 v228, v228, v82
	v_mul_f32_e32 v229, v229, v83
	v_mul_f32_e32 v230, v230, v84
	v_mul_f32_e32 v231, v231, v85
	v_exp_f32_e32 v224, v224
	v_exp_f32_e32 v225, v225
	v_exp_f32_e32 v226, v226
	v_exp_f32_e32 v227, v227
	v_exp_f32_e32 v228, v228
	v_exp_f32_e32 v229, v229
	v_exp_f32_e32 v230, v230
	v_exp_f32_e32 v231, v231
	v_add_f32_e32 v224, 1.0, v224
	v_add_f32_e32 v225, 1.0, v225
	v_add_f32_e32 v226, 1.0, v226
	v_add_f32_e32 v227, 1.0, v227
	v_add_f32_e32 v228, 1.0, v228
	v_add_f32_e32 v229, 1.0, v229
	v_add_f32_e32 v230, 1.0, v230
	v_add_f32_e32 v231, 1.0, v231
	v_rcp_f32_e32 v224, v224
	v_rcp_f32_e32 v225, v225
	v_rcp_f32_e32 v226, v226
	v_rcp_f32_e32 v227, v227
	v_rcp_f32_e32 v228, v228
	v_rcp_f32_e32 v229, v229
	v_rcp_f32_e32 v230, v230
	v_rcp_f32_e32 v231, v231
	v_mul_f32_e32 v86, v86, v224
	v_mul_f32_e32 v87, v87, v225
	v_mul_f32_e32 v88, v88, v226
	v_mul_f32_e32 v89, v89, v227
	v_mul_f32_e32 v82, v82, v228
	v_mul_f32_e32 v83, v83, v229
	v_mul_f32_e32 v84, v84, v230
	v_mul_f32_e32 v85, v85, v231
	v_cvt_pk_bf16_f32 v86, v86, v87
	v_cvt_pk_bf16_f32 v87, v88, v89
	v_cvt_pk_bf16_f32 v88, v82, v83
	v_cvt_pk_bf16_f32 v89, v84, v85
	v_add_u32_e32 v233, 0x408, v144
	v_lshlrev_b32_e32 v234, 10, v233
	v_lshl_add_u64 v[236:237], v[138:139], 0, v[234:235]
	global_store_dwordx4 v[236:237], v[86:89], off
	v_mul_f32_e32 v224, v78, v78
	v_mul_f32_e32 v225, v79, v79
	v_mul_f32_e32 v226, v80, v80
	v_mul_f32_e32 v227, v81, v81
	v_mul_f32_e32 v228, v74, v74
	v_mul_f32_e32 v229, v75, v75
	v_mul_f32_e32 v230, v76, v76
	v_mul_f32_e32 v231, v77, v77
	v_fmaak_f32 v224, v232, v224, 0xc0135761
	v_fmaak_f32 v225, v232, v225, 0xc0135761
	v_fmaak_f32 v226, v232, v226, 0xc0135761
	v_fmaak_f32 v227, v232, v227, 0xc0135761
	v_fmaak_f32 v228, v232, v228, 0xc0135761
	v_fmaak_f32 v229, v232, v229, 0xc0135761
	v_fmaak_f32 v230, v232, v230, 0xc0135761
	v_fmaak_f32 v231, v232, v231, 0xc0135761
	v_mul_f32_e32 v224, v224, v78
	v_mul_f32_e32 v225, v225, v79
	v_mul_f32_e32 v226, v226, v80
	v_mul_f32_e32 v227, v227, v81
	v_mul_f32_e32 v228, v228, v74
	v_mul_f32_e32 v229, v229, v75
	v_mul_f32_e32 v230, v230, v76
	v_mul_f32_e32 v231, v231, v77
	v_exp_f32_e32 v224, v224
	v_exp_f32_e32 v225, v225
	v_exp_f32_e32 v226, v226
	v_exp_f32_e32 v227, v227
	v_exp_f32_e32 v228, v228
	v_exp_f32_e32 v229, v229
	v_exp_f32_e32 v230, v230
	v_exp_f32_e32 v231, v231
	v_add_f32_e32 v224, 1.0, v224
	v_add_f32_e32 v225, 1.0, v225
	v_add_f32_e32 v226, 1.0, v226
	v_add_f32_e32 v227, 1.0, v227
	v_add_f32_e32 v228, 1.0, v228
	v_add_f32_e32 v229, 1.0, v229
	v_add_f32_e32 v230, 1.0, v230
	v_add_f32_e32 v231, 1.0, v231
	v_rcp_f32_e32 v224, v224
	v_rcp_f32_e32 v225, v225
	v_rcp_f32_e32 v226, v226
	v_rcp_f32_e32 v227, v227
	v_rcp_f32_e32 v228, v228
	v_rcp_f32_e32 v229, v229
	v_rcp_f32_e32 v230, v230
	v_rcp_f32_e32 v231, v231
	v_mul_f32_e32 v78, v78, v224
	v_mul_f32_e32 v79, v79, v225
	v_mul_f32_e32 v80, v80, v226
	v_mul_f32_e32 v81, v81, v227
	v_mul_f32_e32 v74, v74, v228
	v_mul_f32_e32 v75, v75, v229
	v_mul_f32_e32 v76, v76, v230
	v_mul_f32_e32 v77, v77, v231
	v_cvt_pk_bf16_f32 v78, v78, v79
	v_cvt_pk_bf16_f32 v79, v80, v81
	v_cvt_pk_bf16_f32 v80, v74, v75
	v_cvt_pk_bf16_f32 v81, v76, v77
	v_add_u32_e32 v233, 0x600, v144
	v_lshlrev_b32_e32 v234, 10, v233
	v_lshl_add_u64 v[236:237], v[138:139], 0, v[234:235]
	global_store_dwordx4 v[236:237], v[78:81], off
	v_mul_f32_e32 v224, v70, v70
	v_mul_f32_e32 v225, v71, v71
	v_mul_f32_e32 v226, v72, v72
	v_mul_f32_e32 v227, v73, v73
	v_mul_f32_e32 v228, v66, v66
	v_mul_f32_e32 v229, v67, v67
	v_mul_f32_e32 v230, v68, v68
	v_mul_f32_e32 v231, v69, v69
	v_fmaak_f32 v224, v232, v224, 0xc0135761
	v_fmaak_f32 v225, v232, v225, 0xc0135761
	v_fmaak_f32 v226, v232, v226, 0xc0135761
	v_fmaak_f32 v227, v232, v227, 0xc0135761
	v_fmaak_f32 v228, v232, v228, 0xc0135761
	v_fmaak_f32 v229, v232, v229, 0xc0135761
	v_fmaak_f32 v230, v232, v230, 0xc0135761
	v_fmaak_f32 v231, v232, v231, 0xc0135761
	v_mul_f32_e32 v224, v224, v70
	v_mul_f32_e32 v225, v225, v71
	v_mul_f32_e32 v226, v226, v72
	v_mul_f32_e32 v227, v227, v73
	v_mul_f32_e32 v228, v228, v66
	v_mul_f32_e32 v229, v229, v67
	v_mul_f32_e32 v230, v230, v68
	v_mul_f32_e32 v231, v231, v69
	v_exp_f32_e32 v224, v224
	v_exp_f32_e32 v225, v225
	v_exp_f32_e32 v226, v226
	v_exp_f32_e32 v227, v227
	v_exp_f32_e32 v228, v228
	v_exp_f32_e32 v229, v229
	v_exp_f32_e32 v230, v230
	v_exp_f32_e32 v231, v231
	v_add_f32_e32 v224, 1.0, v224
	v_add_f32_e32 v225, 1.0, v225
	v_add_f32_e32 v226, 1.0, v226
	v_add_f32_e32 v227, 1.0, v227
	v_add_f32_e32 v228, 1.0, v228
	v_add_f32_e32 v229, 1.0, v229
	v_add_f32_e32 v230, 1.0, v230
	v_add_f32_e32 v231, 1.0, v231
	v_rcp_f32_e32 v224, v224
	v_rcp_f32_e32 v225, v225
	v_rcp_f32_e32 v226, v226
	v_rcp_f32_e32 v227, v227
	v_rcp_f32_e32 v228, v228
	v_rcp_f32_e32 v229, v229
	v_rcp_f32_e32 v230, v230
	v_rcp_f32_e32 v231, v231
	v_mul_f32_e32 v70, v70, v224
	v_mul_f32_e32 v71, v71, v225
	v_mul_f32_e32 v72, v72, v226
	v_mul_f32_e32 v73, v73, v227
	v_mul_f32_e32 v66, v66, v228
; __device__ __forceinline__ unsigned cvt_pk_bf16(float lo, float hi) { unsigned r; asm volatile("v_cvt_pk_bf16_f32 %0, %1, %2" : "=v"(r) : "v"(lo), "v"(hi)); return r; }
; __device__ __forceinline__ float sigmoid_f(float x) { return __builtin_amdgcn_rcpf(1.0f + __builtin_amdgcn_exp2f(-1.4426950408889634f * x)); }
;     __device__ __forceinline__ void operator()(const f32x4 (&acc)[2][2][4][2], const pg8::Unit& u, int wr, int wc, int fr, int fq, LAS unsigned char* lds, int wid, int lane, const pg8::Unit& nxt, bool has_next, int ui) const {
;     ...
;                 const int tok0 = (rl0 + ai * 128 + m * 16) * TC;
; #pragma unroll
;                 for (int bj = 0; bj < 2; ++bj) {
;                     const int t = 16 * pnl + 8 * bj + 2 * wc + (fq >> 1), h0 = 8 * (fq & 1);
;                     float o[8];
; #pragma unroll
;                     for (int e = 0; e < 8; ++e) { const float y = acc[ai][bj][m][e >> 2][e & 3]; o[e] = y * sigmoid_f(1.5957691216f * y * (1.0f + 0.044715f * y * y)); }
;                     v4u w; w.x = cvt_pk_bf16(o[0], o[1]); w.y = cvt_pk_bf16(o[2], o[3]); w.z = cvt_pk_bf16(o[4], o[5]); w.w = cvt_pk_bf16(o[6], o[7]);
;                     *(v4u*)(Z + ((size_t)(tok0 + t) * SW + gg * 16 + h0)) = w;
;                 }
	v_mul_f32_e32 v67, v67, v229
	v_mul_f32_e32 v68, v68, v230
	v_mul_f32_e32 v69, v69, v231
	v_cvt_pk_bf16_f32 v70, v70, v71
	v_cvt_pk_bf16_f32 v71, v72, v73
	v_cvt_pk_bf16_f32 v72, v66, v67
	v_cvt_pk_bf16_f32 v73, v68, v69
	v_add_u32_e32 v233, 0x608, v144
	v_lshlrev_b32_e32 v234, 10, v233
	v_lshl_add_u64 v[236:237], v[138:139], 0, v[234:235]
	global_store_dwordx4 v[236:237], v[70:73], off
	v_mul_f32_e32 v224, v62, v62
	v_mul_f32_e32 v225, v63, v63
	v_mul_f32_e32 v226, v64, v64
	v_mul_f32_e32 v227, v65, v65
	v_mul_f32_e32 v228, v58, v58
	v_mul_f32_e32 v229, v59, v59
	v_mul_f32_e32 v230, v60, v60
	v_mul_f32_e32 v231, v61, v61
	v_fmaak_f32 v224, v232, v224, 0xc0135761
	v_fmaak_f32 v225, v232, v225, 0xc0135761
	v_fmaak_f32 v226, v232, v226, 0xc0135761
	v_fmaak_f32 v227, v232, v227, 0xc0135761
	v_fmaak_f32 v228, v232, v228, 0xc0135761
	v_fmaak_f32 v229, v232, v229, 0xc0135761
	v_fmaak_f32 v230, v232, v230, 0xc0135761
	v_fmaak_f32 v231, v232, v231, 0xc0135761
	v_mul_f32_e32 v224, v224, v62
	v_mul_f32_e32 v225, v225, v63
	v_mul_f32_e32 v226, v226, v64
	v_mul_f32_e32 v227, v227, v65
	v_mul_f32_e32 v228, v228, v58
	v_mul_f32_e32 v229, v229, v59
	v_mul_f32_e32 v230, v230, v60
	v_mul_f32_e32 v231, v231, v61
	v_exp_f32_e32 v224, v224
	v_exp_f32_e32 v225, v225
	v_exp_f32_e32 v226, v226
	v_exp_f32_e32 v227, v227
	v_exp_f32_e32 v228, v228
	v_exp_f32_e32 v229, v229
	v_exp_f32_e32 v230, v230
	v_exp_f32_e32 v231, v231
	v_add_f32_e32 v224, 1.0, v224
	v_add_f32_e32 v225, 1.0, v225
	v_add_f32_e32 v226, 1.0, v226
	v_add_f32_e32 v227, 1.0, v227
	v_add_f32_e32 v228, 1.0, v228
	v_add_f32_e32 v229, 1.0, v229
	v_add_f32_e32 v230, 1.0, v230
	v_add_f32_e32 v231, 1.0, v231
	v_rcp_f32_e32 v224, v224
	v_rcp_f32_e32 v225, v225
	v_rcp_f32_e32 v226, v226
	v_rcp_f32_e32 v227, v227
	v_rcp_f32_e32 v228, v228
	v_rcp_f32_e32 v229, v229
	v_rcp_f32_e32 v230, v230
	v_rcp_f32_e32 v231, v231
	v_mul_f32_e32 v62, v62, v224
	v_mul_f32_e32 v63, v63, v225
	v_mul_f32_e32 v64, v64, v226
	v_mul_f32_e32 v65, v65, v227
	v_mul_f32_e32 v58, v58, v228
	v_mul_f32_e32 v59, v59, v229
	v_mul_f32_e32 v60, v60, v230
	v_mul_f32_e32 v61, v61, v231
	v_cvt_pk_bf16_f32 v62, v62, v63
	v_cvt_pk_bf16_f32 v63, v64, v65
	v_cvt_pk_bf16_f32 v64, v58, v59
	v_cvt_pk_bf16_f32 v65, v60, v61
	v_add_u32_e32 v233, 0x1000, v144
	v_lshlrev_b32_e32 v234, 10, v233
	v_lshl_add_u64 v[236:237], v[138:139], 0, v[234:235]
	global_store_dwordx4 v[236:237], v[62:65], off
	v_mul_f32_e32 v224, v54, v54
	v_mul_f32_e32 v225, v55, v55
	v_mul_f32_e32 v226, v56, v56
	v_mul_f32_e32 v227, v57, v57
	v_mul_f32_e32 v228, v50, v50
	v_mul_f32_e32 v229, v51, v51
	v_mul_f32_e32 v230, v52, v52
	v_mul_f32_e32 v231, v53, v53
	v_fmaak_f32 v224, v232, v224, 0xc0135761
	v_fmaak_f32 v225, v232, v225, 0xc0135761
	v_fmaak_f32 v226, v232, v226, 0xc0135761
	v_fmaak_f32 v227, v232, v227, 0xc0135761
	v_fmaak_f32 v228, v232, v228, 0xc0135761
	v_fmaak_f32 v229, v232, v229, 0xc0135761
	v_fmaak_f32 v230, v232, v230, 0xc0135761
	v_fmaak_f32 v231, v232, v231, 0xc0135761
	v_mul_f32_e32 v224, v224, v54
	v_mul_f32_e32 v225, v225, v55
	v_mul_f32_e32 v226, v226, v56
	v_mul_f32_e32 v227, v227, v57
	v_mul_f32_e32 v228, v228, v50
	v_mul_f32_e32 v229, v229, v51
	v_mul_f32_e32 v230, v230, v52
	v_mul_f32_e32 v231, v231, v53
	v_exp_f32_e32 v224, v224
	v_exp_f32_e32 v225, v225
	v_exp_f32_e32 v226, v226
	v_exp_f32_e32 v227, v227
	v_exp_f32_e32 v228, v228
	v_exp_f32_e32 v229, v229
	v_exp_f32_e32 v230, v230
	v_exp_f32_e32 v231, v231
	v_add_f32_e32 v224, 1.0, v224
	v_add_f32_e32 v225, 1.0, v225
	v_add_f32_e32 v226, 1.0, v226
	v_add_f32_e32 v227, 1.0, v227
	v_add_f32_e32 v228, 1.0, v228
	v_add_f32_e32 v229, 1.0, v229
	v_add_f32_e32 v230, 1.0, v230
	v_add_f32_e32 v231, 1.0, v231
	v_rcp_f32_e32 v224, v224
	v_rcp_f32_e32 v225, v225
	v_rcp_f32_e32 v226, v226
	v_rcp_f32_e32 v227, v227
	v_rcp_f32_e32 v228, v228
	v_rcp_f32_e32 v229, v229
	v_rcp_f32_e32 v230, v230
	v_rcp_f32_e32 v231, v231
	v_mul_f32_e32 v54, v54, v224
	v_mul_f32_e32 v55, v55, v225
	v_mul_f32_e32 v56, v56, v226
	v_mul_f32_e32 v57, v57, v227
	v_mul_f32_e32 v50, v50, v228
	v_mul_f32_e32 v51, v51, v229
	v_mul_f32_e32 v52, v52, v230
	v_mul_f32_e32 v53, v53, v231
	v_cvt_pk_bf16_f32 v54, v54, v55
	v_cvt_pk_bf16_f32 v55, v56, v57
	v_cvt_pk_bf16_f32 v56, v50, v51
	v_cvt_pk_bf16_f32 v57, v52, v53
	v_add_u32_e32 v233, 0x1008, v144
	v_lshlrev_b32_e32 v234, 10, v233
	v_lshl_add_u64 v[236:237], v[138:139], 0, v[234:235]
	global_store_dwordx4 v[236:237], v[54:57], off
	v_mul_f32_e32 v224, v46, v46
	v_mul_f32_e32 v225, v47, v47
	v_mul_f32_e32 v226, v48, v48
	v_mul_f32_e32 v227, v49, v49
	v_mul_f32_e32 v228, v42, v42
	v_mul_f32_e32 v229, v43, v43
	v_mul_f32_e32 v230, v44, v44
	v_mul_f32_e32 v231, v45, v45
	v_fmaak_f32 v224, v232, v224, 0xc0135761
	v_fmaak_f32 v225, v232, v225, 0xc0135761
	v_fmaak_f32 v226, v232, v226, 0xc0135761
	v_fmaak_f32 v227, v232, v227, 0xc0135761
	v_fmaak_f32 v228, v232, v228, 0xc0135761
	v_fmaak_f32 v229, v232, v229, 0xc0135761
	v_fmaak_f32 v230, v232, v230, 0xc0135761
	v_fmaak_f32 v231, v232, v231, 0xc0135761
	v_mul_f32_e32 v224, v224, v46
	v_mul_f32_e32 v225, v225, v47
	v_mul_f32_e32 v226, v226, v48
	v_mul_f32_e32 v227, v227, v49
	v_mul_f32_e32 v228, v228, v42
	v_mul_f32_e32 v229, v229, v43
	v_mul_f32_e32 v230, v230, v44
	v_mul_f32_e32 v231, v231, v45
	v_exp_f32_e32 v224, v224
	v_exp_f32_e32 v225, v225
	v_exp_f32_e32 v226, v226
	v_exp_f32_e32 v227, v227
	v_exp_f32_e32 v228, v228
	v_exp_f32_e32 v229, v229
	v_exp_f32_e32 v230, v230
	v_exp_f32_e32 v231, v231
	v_add_f32_e32 v224, 1.0, v224
	v_add_f32_e32 v225, 1.0, v225
	v_add_f32_e32 v226, 1.0, v226
	v_add_f32_e32 v227, 1.0, v227
	v_add_f32_e32 v228, 1.0, v228
; __device__ __forceinline__ unsigned cvt_pk_bf16(float lo, float hi) { unsigned r; asm volatile("v_cvt_pk_bf16_f32 %0, %1, %2" : "=v"(r) : "v"(lo), "v"(hi)); return r; }
; __device__ __forceinline__ float sigmoid_f(float x) { return __builtin_amdgcn_rcpf(1.0f + __builtin_amdgcn_exp2f(-1.4426950408889634f * x)); }
;     __device__ __forceinline__ void operator()(const f32x4 (&acc)[2][2][4][2], const pg8::Unit& u, int wr, int wc, int fr, int fq, LAS unsigned char* lds, int wid, int lane, const pg8::Unit& nxt, bool has_next, int ui) const {
;     ...
;                 const int tok0 = (rl0 + ai * 128 + m * 16) * TC;
; #pragma unroll
;                 for (int bj = 0; bj < 2; ++bj) {
;                     const int t = 16 * pnl + 8 * bj + 2 * wc + (fq >> 1), h0 = 8 * (fq & 1);
;                     float o[8];
; #pragma unroll
;                     for (int e = 0; e < 8; ++e) { const float y = acc[ai][bj][m][e >> 2][e & 3]; o[e] = y * sigmoid_f(1.5957691216f * y * (1.0f + 0.044715f * y * y)); }
;                     v4u w; w.x = cvt_pk_bf16(o[0], o[1]); w.y = cvt_pk_bf16(o[2], o[3]); w.z = cvt_pk_bf16(o[4], o[5]); w.w = cvt_pk_bf16(o[6], o[7]);
;                     *(v4u*)(Z + ((size_t)(tok0 + t) * SW + gg * 16 + h0)) = w;
;                 }
	v_add_f32_e32 v229, 1.0, v229
	v_add_f32_e32 v230, 1.0, v230
	v_add_f32_e32 v231, 1.0, v231
	v_rcp_f32_e32 v224, v224
	v_rcp_f32_e32 v225, v225
	v_rcp_f32_e32 v226, v226
	v_rcp_f32_e32 v227, v227
	v_rcp_f32_e32 v228, v228
	v_rcp_f32_e32 v229, v229
	v_rcp_f32_e32 v230, v230
	v_rcp_f32_e32 v231, v231
	v_mul_f32_e32 v46, v46, v224
	v_mul_f32_e32 v47, v47, v225
	v_mul_f32_e32 v48, v48, v226
	v_mul_f32_e32 v49, v49, v227
	v_mul_f32_e32 v42, v42, v228
	v_mul_f32_e32 v43, v43, v229
	v_mul_f32_e32 v44, v44, v230
	v_mul_f32_e32 v45, v45, v231
	v_cvt_pk_bf16_f32 v46, v46, v47
	v_cvt_pk_bf16_f32 v47, v48, v49
	v_cvt_pk_bf16_f32 v48, v42, v43
	v_cvt_pk_bf16_f32 v49, v44, v45
	v_add_u32_e32 v233, 0x1200, v144
	v_lshlrev_b32_e32 v234, 10, v233
	v_lshl_add_u64 v[236:237], v[138:139], 0, v[234:235]
	global_store_dwordx4 v[236:237], v[46:49], off
	v_mul_f32_e32 v224, v38, v38
	v_mul_f32_e32 v225, v39, v39
	v_mul_f32_e32 v226, v40, v40
	v_mul_f32_e32 v227, v41, v41
	v_mul_f32_e32 v228, v34, v34
	v_mul_f32_e32 v229, v35, v35
	v_mul_f32_e32 v230, v36, v36
	v_mul_f32_e32 v231, v37, v37
	v_fmaak_f32 v224, v232, v224, 0xc0135761
	v_fmaak_f32 v225, v232, v225, 0xc0135761
	v_fmaak_f32 v226, v232, v226, 0xc0135761
	v_fmaak_f32 v227, v232, v227, 0xc0135761
	v_fmaak_f32 v228, v232, v228, 0xc0135761
	v_fmaak_f32 v229, v232, v229, 0xc0135761
	v_fmaak_f32 v230, v232, v230, 0xc0135761
	v_fmaak_f32 v231, v232, v231, 0xc0135761
	v_mul_f32_e32 v224, v224, v38
	v_mul_f32_e32 v225, v225, v39
	v_mul_f32_e32 v226, v226, v40
	v_mul_f32_e32 v227, v227, v41
	v_mul_f32_e32 v228, v228, v34
	v_mul_f32_e32 v229, v229, v35
	v_mul_f32_e32 v230, v230, v36
	v_mul_f32_e32 v231, v231, v37
	v_exp_f32_e32 v224, v224
	v_exp_f32_e32 v225, v225
	v_exp_f32_e32 v226, v226
	v_exp_f32_e32 v227, v227
	v_exp_f32_e32 v228, v228
	v_exp_f32_e32 v229, v229
	v_exp_f32_e32 v230, v230
	v_exp_f32_e32 v231, v231
	v_add_f32_e32 v224, 1.0, v224
	v_add_f32_e32 v225, 1.0, v225
	v_add_f32_e32 v226, 1.0, v226
	v_add_f32_e32 v227, 1.0, v227
	v_add_f32_e32 v228, 1.0, v228
	v_add_f32_e32 v229, 1.0, v229
	v_add_f32_e32 v230, 1.0, v230
	v_add_f32_e32 v231, 1.0, v231
	v_rcp_f32_e32 v224, v224
	v_rcp_f32_e32 v225, v225
	v_rcp_f32_e32 v226, v226
	v_rcp_f32_e32 v227, v227
	v_rcp_f32_e32 v228, v228
	v_rcp_f32_e32 v229, v229
	v_rcp_f32_e32 v230, v230
	v_rcp_f32_e32 v231, v231
	v_mul_f32_e32 v38, v38, v224
	v_mul_f32_e32 v39, v39, v225
	v_mul_f32_e32 v40, v40, v226
	v_mul_f32_e32 v41, v41, v227
	v_mul_f32_e32 v34, v34, v228
	v_mul_f32_e32 v35, v35, v229
	v_mul_f32_e32 v36, v36, v230
	v_mul_f32_e32 v37, v37, v231
	v_cvt_pk_bf16_f32 v38, v38, v39
	v_cvt_pk_bf16_f32 v39, v40, v41
	v_cvt_pk_bf16_f32 v40, v34, v35
	v_cvt_pk_bf16_f32 v41, v36, v37
	v_add_u32_e32 v233, 0x1208, v144
	v_lshlrev_b32_e32 v234, 10, v233
	v_lshl_add_u64 v[236:237], v[138:139], 0, v[234:235]
	global_store_dwordx4 v[236:237], v[38:41], off
	v_mul_f32_e32 v224, v30, v30
	v_mul_f32_e32 v225, v31, v31
	v_mul_f32_e32 v226, v32, v32
	v_mul_f32_e32 v227, v33, v33
	v_mul_f32_e32 v228, v26, v26
	v_mul_f32_e32 v229, v27, v27
	v_mul_f32_e32 v230, v28, v28
	v_mul_f32_e32 v231, v29, v29
	v_fmaak_f32 v224, v232, v224, 0xc0135761
	v_fmaak_f32 v225, v232, v225, 0xc0135761
	v_fmaak_f32 v226, v232, v226, 0xc0135761
	v_fmaak_f32 v227, v232, v227, 0xc0135761
	v_fmaak_f32 v228, v232, v228, 0xc0135761
	v_fmaak_f32 v229, v232, v229, 0xc0135761
	v_fmaak_f32 v230, v232, v230, 0xc0135761
	v_fmaak_f32 v231, v232, v231, 0xc0135761
	v_mul_f32_e32 v224, v224, v30
	v_mul_f32_e32 v225, v225, v31
	v_mul_f32_e32 v226, v226, v32
	v_mul_f32_e32 v227, v227, v33
	v_mul_f32_e32 v228, v228, v26
	v_mul_f32_e32 v229, v229, v27
	v_mul_f32_e32 v230, v230, v28
	v_mul_f32_e32 v231, v231, v29
	v_exp_f32_e32 v224, v224
	v_exp_f32_e32 v225, v225
	v_exp_f32_e32 v226, v226
	v_exp_f32_e32 v227, v227
	v_exp_f32_e32 v228, v228
	v_exp_f32_e32 v229, v229
	v_exp_f32_e32 v230, v230
	v_exp_f32_e32 v231, v231
	v_add_f32_e32 v224, 1.0, v224
	v_add_f32_e32 v225, 1.0, v225
	v_add_f32_e32 v226, 1.0, v226
	v_add_f32_e32 v227, 1.0, v227
	v_add_f32_e32 v228, 1.0, v228
	v_add_f32_e32 v229, 1.0, v229
	v_add_f32_e32 v230, 1.0, v230
	v_add_f32_e32 v231, 1.0, v231
	v_rcp_f32_e32 v224, v224
	v_rcp_f32_e32 v225, v225
	v_rcp_f32_e32 v226, v226
	v_rcp_f32_e32 v227, v227
	v_rcp_f32_e32 v228, v228
	v_rcp_f32_e32 v229, v229
	v_rcp_f32_e32 v230, v230
	v_rcp_f32_e32 v231, v231
	v_mul_f32_e32 v30, v30, v224
	v_mul_f32_e32 v31, v31, v225
	v_mul_f32_e32 v32, v32, v226
	v_mul_f32_e32 v33, v33, v227
	v_mul_f32_e32 v26, v26, v228
	v_mul_f32_e32 v27, v27, v229
	v_mul_f32_e32 v28, v28, v230
	v_mul_f32_e32 v29, v29, v231
	v_cvt_pk_bf16_f32 v30, v30, v31
	v_cvt_pk_bf16_f32 v31, v32, v33
	v_cvt_pk_bf16_f32 v32, v26, v27
	v_cvt_pk_bf16_f32 v33, v28, v29
	v_add_u32_e32 v233, 0x1400, v144
	v_lshlrev_b32_e32 v234, 10, v233
	v_lshl_add_u64 v[236:237], v[138:139], 0, v[234:235]
	global_store_dwordx4 v[236:237], v[30:33], off
	v_mul_f32_e32 v224, v22, v22
	v_mul_f32_e32 v225, v23, v23
	v_mul_f32_e32 v226, v24, v24
	v_mul_f32_e32 v227, v25, v25
	v_mul_f32_e32 v228, v18, v18
	v_mul_f32_e32 v229, v19, v19
	v_mul_f32_e32 v230, v20, v20
	v_mul_f32_e32 v231, v21, v21
	v_fmaak_f32 v224, v232, v224, 0xc0135761
	v_fmaak_f32 v225, v232, v225, 0xc0135761
	v_fmaak_f32 v226, v232, v226, 0xc0135761
	v_fmaak_f32 v227, v232, v227, 0xc0135761
	v_fmaak_f32 v228, v232, v228, 0xc0135761
	v_fmaak_f32 v229, v232, v229, 0xc0135761
	v_fmaak_f32 v230, v232, v230, 0xc0135761
	v_fmaak_f32 v231, v232, v231, 0xc0135761
	v_mul_f32_e32 v224, v224, v22
	v_mul_f32_e32 v225, v225, v23
; __device__ __forceinline__ unsigned cvt_pk_bf16(float lo, float hi) { unsigned r; asm volatile("v_cvt_pk_bf16_f32 %0, %1, %2" : "=v"(r) : "v"(lo), "v"(hi)); return r; }
; __device__ __forceinline__ float sigmoid_f(float x) { return __builtin_amdgcn_rcpf(1.0f + __builtin_amdgcn_exp2f(-1.4426950408889634f * x)); }
;     __device__ __forceinline__ void operator()(const f32x4 (&acc)[2][2][4][2], const pg8::Unit& u, int wr, int wc, int fr, int fq, LAS unsigned char* lds, int wid, int lane, const pg8::Unit& nxt, bool has_next, int ui) const {
;     ...
;                 const int tok0 = (rl0 + ai * 128 + m * 16) * TC;
; #pragma unroll
;                 for (int bj = 0; bj < 2; ++bj) {
;                     const int t = 16 * pnl + 8 * bj + 2 * wc + (fq >> 1), h0 = 8 * (fq & 1);
;                     float o[8];
; #pragma unroll
;                     for (int e = 0; e < 8; ++e) { const float y = acc[ai][bj][m][e >> 2][e & 3]; o[e] = y * sigmoid_f(1.5957691216f * y * (1.0f + 0.044715f * y * y)); }
;                     v4u w; w.x = cvt_pk_bf16(o[0], o[1]); w.y = cvt_pk_bf16(o[2], o[3]); w.z = cvt_pk_bf16(o[4], o[5]); w.w = cvt_pk_bf16(o[6], o[7]);
;                     *(v4u*)(Z + ((size_t)(tok0 + t) * SW + gg * 16 + h0)) = w;
;                 }
	v_mul_f32_e32 v226, v226, v24
	v_mul_f32_e32 v227, v227, v25
	v_mul_f32_e32 v228, v228, v18
	v_mul_f32_e32 v229, v229, v19
	v_mul_f32_e32 v230, v230, v20
	v_mul_f32_e32 v231, v231, v21
	v_exp_f32_e32 v224, v224
	v_exp_f32_e32 v225, v225
	v_exp_f32_e32 v226, v226
	v_exp_f32_e32 v227, v227
	v_exp_f32_e32 v228, v228
	v_exp_f32_e32 v229, v229
	v_exp_f32_e32 v230, v230
	v_exp_f32_e32 v231, v231
	v_add_f32_e32 v224, 1.0, v224
	v_add_f32_e32 v225, 1.0, v225
	v_add_f32_e32 v226, 1.0, v226
	v_add_f32_e32 v227, 1.0, v227
	v_add_f32_e32 v228, 1.0, v228
	v_add_f32_e32 v229, 1.0, v229
	v_add_f32_e32 v230, 1.0, v230
	v_add_f32_e32 v231, 1.0, v231
	v_rcp_f32_e32 v224, v224
	v_rcp_f32_e32 v225, v225
	v_rcp_f32_e32 v226, v226
	v_rcp_f32_e32 v227, v227
	v_rcp_f32_e32 v228, v228
	v_rcp_f32_e32 v229, v229
	v_rcp_f32_e32 v230, v230
	v_rcp_f32_e32 v231, v231
	v_mul_f32_e32 v22, v22, v224
	v_mul_f32_e32 v23, v23, v225
	v_mul_f32_e32 v24, v24, v226
	v_mul_f32_e32 v25, v25, v227
	v_mul_f32_e32 v18, v18, v228
	v_mul_f32_e32 v19, v19, v229
	v_mul_f32_e32 v20, v20, v230
	v_mul_f32_e32 v21, v21, v231
	v_cvt_pk_bf16_f32 v22, v22, v23
	v_cvt_pk_bf16_f32 v23, v24, v25
	v_cvt_pk_bf16_f32 v24, v18, v19
	v_cvt_pk_bf16_f32 v25, v20, v21
	v_add_u32_e32 v233, 0x1408, v144
	v_lshlrev_b32_e32 v234, 10, v233
	v_lshl_add_u64 v[236:237], v[138:139], 0, v[234:235]
	global_store_dwordx4 v[236:237], v[22:25], off
	v_mul_f32_e32 v224, v14, v14
	v_mul_f32_e32 v225, v15, v15
	v_mul_f32_e32 v226, v16, v16
	v_mul_f32_e32 v227, v17, v17
	v_mul_f32_e32 v228, v10, v10
	v_mul_f32_e32 v229, v11, v11
	v_mul_f32_e32 v230, v12, v12
	v_mul_f32_e32 v231, v13, v13
	v_fmaak_f32 v224, v232, v224, 0xc0135761
	v_fmaak_f32 v225, v232, v225, 0xc0135761
	v_fmaak_f32 v226, v232, v226, 0xc0135761
	v_fmaak_f32 v227, v232, v227, 0xc0135761
	v_fmaak_f32 v228, v232, v228, 0xc0135761
	v_fmaak_f32 v229, v232, v229, 0xc0135761
	v_fmaak_f32 v230, v232, v230, 0xc0135761
	v_fmaak_f32 v231, v232, v231, 0xc0135761
	v_mul_f32_e32 v224, v224, v14
	v_mul_f32_e32 v225, v225, v15
	v_mul_f32_e32 v226, v226, v16
	v_mul_f32_e32 v227, v227, v17
	v_mul_f32_e32 v228, v228, v10
	v_mul_f32_e32 v229, v229, v11
	v_mul_f32_e32 v230, v230, v12
	v_mul_f32_e32 v231, v231, v13
	v_exp_f32_e32 v224, v224
	v_exp_f32_e32 v225, v225
	v_exp_f32_e32 v226, v226
	v_exp_f32_e32 v227, v227
	v_exp_f32_e32 v228, v228
	v_exp_f32_e32 v229, v229
	v_exp_f32_e32 v230, v230
	v_exp_f32_e32 v231, v231
	v_add_f32_e32 v224, 1.0, v224
	v_add_f32_e32 v225, 1.0, v225
	v_add_f32_e32 v226, 1.0, v226
	v_add_f32_e32 v227, 1.0, v227
	v_add_f32_e32 v228, 1.0, v228
	v_add_f32_e32 v229, 1.0, v229
	v_add_f32_e32 v230, 1.0, v230
	v_add_f32_e32 v231, 1.0, v231
	v_rcp_f32_e32 v224, v224
	v_rcp_f32_e32 v225, v225
	v_rcp_f32_e32 v226, v226
	v_rcp_f32_e32 v227, v227
	v_rcp_f32_e32 v228, v228
	v_rcp_f32_e32 v229, v229
	v_rcp_f32_e32 v230, v230
	v_rcp_f32_e32 v231, v231
	v_mul_f32_e32 v14, v14, v224
	v_mul_f32_e32 v15, v15, v225
	v_mul_f32_e32 v16, v16, v226
	v_mul_f32_e32 v17, v17, v227
	v_mul_f32_e32 v10, v10, v228
	v_mul_f32_e32 v11, v11, v229
	v_mul_f32_e32 v12, v12, v230
	v_mul_f32_e32 v13, v13, v231
	v_cvt_pk_bf16_f32 v14, v14, v15
	v_cvt_pk_bf16_f32 v15, v16, v17
	v_cvt_pk_bf16_f32 v16, v10, v11
	v_cvt_pk_bf16_f32 v17, v12, v13
	v_add_u32_e32 v233, 0x1600, v144
	v_lshlrev_b32_e32 v234, 10, v233
	v_lshl_add_u64 v[236:237], v[138:139], 0, v[234:235]
	global_store_dwordx4 v[236:237], v[14:17], off
	v_mul_f32_e32 v224, v6, v6
	v_mul_f32_e32 v225, v7, v7
	v_mul_f32_e32 v226, v8, v8
	v_mul_f32_e32 v227, v9, v9
	v_mul_f32_e32 v228, v2, v2
	v_mul_f32_e32 v229, v3, v3
	v_mul_f32_e32 v230, v4, v4
	v_mul_f32_e32 v231, v5, v5
	v_fmaak_f32 v224, v232, v224, 0xc0135761
	v_fmaak_f32 v225, v232, v225, 0xc0135761
	v_fmaak_f32 v226, v232, v226, 0xc0135761
	v_fmaak_f32 v227, v232, v227, 0xc0135761
	v_fmaak_f32 v228, v232, v228, 0xc0135761
	v_fmaak_f32 v229, v232, v229, 0xc0135761
	v_fmaak_f32 v230, v232, v230, 0xc0135761
	v_fmaak_f32 v231, v232, v231, 0xc0135761
	v_mul_f32_e32 v224, v224, v6
	v_mul_f32_e32 v225, v225, v7
	v_mul_f32_e32 v226, v226, v8
	v_mul_f32_e32 v227, v227, v9
	v_mul_f32_e32 v228, v228, v2
	v_mul_f32_e32 v229, v229, v3
	v_mul_f32_e32 v230, v230, v4
	v_mul_f32_e32 v231, v231, v5
	v_exp_f32_e32 v224, v224
	v_exp_f32_e32 v225, v225
	v_exp_f32_e32 v226, v226
	v_exp_f32_e32 v227, v227
	v_exp_f32_e32 v228, v228
	v_exp_f32_e32 v229, v229
	v_exp_f32_e32 v230, v230
	v_exp_f32_e32 v231, v231
	v_add_f32_e32 v224, 1.0, v224
	v_add_f32_e32 v225, 1.0, v225
	v_add_f32_e32 v226, 1.0, v226
	v_add_f32_e32 v227, 1.0, v227
	v_add_f32_e32 v228, 1.0, v228
	v_add_f32_e32 v229, 1.0, v229
	v_add_f32_e32 v230, 1.0, v230
	v_add_f32_e32 v231, 1.0, v231
	v_rcp_f32_e32 v224, v224
	v_rcp_f32_e32 v225, v225
	v_rcp_f32_e32 v226, v226
	v_rcp_f32_e32 v227, v227
	v_rcp_f32_e32 v228, v228
	v_rcp_f32_e32 v229, v229
	v_rcp_f32_e32 v230, v230
	v_rcp_f32_e32 v231, v231
	v_mul_f32_e32 v6, v6, v224
	v_mul_f32_e32 v7, v7, v225
	v_mul_f32_e32 v8, v8, v226
	v_mul_f32_e32 v9, v9, v227
	v_mul_f32_e32 v2, v2, v228
	v_mul_f32_e32 v3, v3, v229
	v_mul_f32_e32 v4, v4, v230
	v_mul_f32_e32 v5, v5, v231
	v_cvt_pk_bf16_f32 v6, v6, v7
	v_cvt_pk_bf16_f32 v7, v8, v9
	v_cvt_pk_bf16_f32 v8, v2, v3
	v_cvt_pk_bf16_f32 v9, v4, v5
	v_add_u32_e32 v233, 0x1608, v144
	v_lshlrev_b32_e32 v234, 10, v233
	v_lshl_add_u64 v[236:237], v[138:139], 0, v[234:235]
	global_store_dwordx4 v[236:237], v[6:9], off
	s_andn2_b64 vcc, exec, s[6:7]
	s_mov_b64 s[10:11], -1
	s_cbranch_vccnz .LBB0_254
	s_andn2_b64 vcc, exec, s[0:1]
	s_cbranch_vccnz .LBB0_253
	s_barrier
	s_branch .LBB0_253
